# inproj XCD-aware mapping, variant: each XCD takes 6 of the 24 N-tiles and half of the M-tiles (weights 1.5 MB per XCD, an xn row tile goes to 4 L2s)
# speedup vs baseline: 1.0016x; 1.0016x over previous
; #define G_STORE(S, bf) { *(uint4*)&s->a[bf][srow][skc] = S##a0; *(uint4*)&s->a[bf][srow + 32][skc] = S##a1; \
;     if (MB == 2) { *(uint4*)&s->a[bf][srow + 64][skc] = S##a2; *(uint4*)&s->a[bf][srow + 96][skc] = S##a3; } \
;     *(uint4*)&s->b[bf][srow][skc] = S##b0; *(uint4*)&s->b[bf][srow + 32][skc] = S##b1; *(uint4*)&s->b[bf][srow + 64][skc] = S##b2; *(uint4*)&s->b[bf][srow + 96][skc] = S##b3; }
; template <int MB, bool PF2 = true>
; DI void gemm_main(const u16* __restrict__ A, int lda, const u16* __restrict__ B, int ldb, int K, f32x16 (&acc)[MB][2], GemmLds* s, int tid) {
;     ...
;   G_LOAD(p, 0); G_STORE(p, 0);
;   if (!PF2) {
;     __syncthreads();
;     for (int kt = 0; kt < KT; kt++) {
;       const int buf = kt & 1;
;       if (kt + 1 < KT) G_LOAD(p, (kt + 1) * 64);
;       if (buf) { G_COMPUTE(1); } else { G_COMPUTE(0); }
;       if (kt + 1 < KT) { if (buf) { G_STORE(p, 0); } else { G_STORE(p, 1); } }
;       __syncthreads();
;     }
;     return;
;   }
;   const int klast = K - 64;
;   G_LOAD(p, 64);
; DI void phase_inproj(const Params& p, int l, char* smem, int tid) {
;     ...
;   for (int it = blockIdx.x; it < 272 * 24; it += gridDim.x) {
;     const int mt = it / 24, nt = it % 24, m0 = mt * 128, n0 = nt * 128;
;     f32x16 acc[2][2]; zero_acc<2>(acc);
;     gemm_main<2>(p.xn + (size_t)m0 * 1024, 1024, Wt + (size_t)n0 * 1024, 1024, 1024, acc, s, tid);
.Lipx_wait:
	s_barrier
	v_mov_b32_e32 v116, 0x125f0
	ds_read_b32 v115, v116
	ds_read_b32 v114, v116 offset:16
	s_waitcnt lgkmcnt(0)
	v_readfirstlane_b32 s12, v115
	v_readfirstlane_b32 s17, v114
	s_lshr_b32 s2, s16, 2
	s_lshl_b32 s2, s2, 8
	s_or_b32 s17, s17, s2
	s_and_b32 s2, s16, 3
	s_mul_i32 s2, s2, 6
	s_lshl_b32 s2, s2, 16
	s_or_b32 s17, s17, s2
	s_cmpk_lt_u32 s12, 0x330
	s_cbranch_scc0 .Lip_done
	s_mul_hi_u32 s0, s12, 0xaaaaaaab
	s_lshr_b32 s0, s0, 2
	s_mul_i32 s2, s0, 6
	s_sub_u32 s1, s12, s2
	s_bfe_u32 s2, s17, 0x80010
	s_add_u32 s1, s1, s2
	s_lshl_b32 s0, s0, 1
	s_bfe_u32 s2, s17, 0x80008
	s_add_u32 s0, s0, s2
	s_lshl_b32 s2, s0, 18
	s_add_u32 s4, s96, s2
	s_addc_u32 s5, s97, 0
	s_lshl_b32 s2, s1, 18
	s_add_u32 s8, s14, s2
	s_addc_u32 s9, s15, 0
	s_add_u32 m0, s10, 0x0
	s_nop 0
	global_load_lds_dwordx4 v98, s[4:5]
	s_add_u32 m0, s10, 0x400
	s_nop 0
	global_load_lds_dwordx4 v99, s[4:5]
	s_add_u32 m0, s10, 0x800
	s_nop 0
	global_load_lds_dwordx4 v100, s[4:5]
	s_add_u32 m0, s10, 0xc00
	s_nop 0
	global_load_lds_dwordx4 v101, s[4:5]
	s_add_u32 m0, s10, 0x4000
	s_nop 0
	global_load_lds_dwordx4 v98, s[8:9]
	s_add_u32 m0, s10, 0x4400
	s_nop 0
	global_load_lds_dwordx4 v99, s[8:9]
	s_add_u32 m0, s10, 0x4800
	s_nop 0
	global_load_lds_dwordx4 v100, s[8:9]
	s_add_u32 m0, s10, 0x4c00
	s_nop 0
	global_load_lds_dwordx4 v101, s[8:9]
	s_add_u32 s4, s4, 128
	s_addc_u32 s5, s5, 0
	s_add_u32 s8, s8, 128
	s_addc_u32 s9, s9, 0
.Lip_item:
	s_mul_hi_u32 s0, s12, 0xaaaaaaab
	s_lshr_b32 s0, s0, 2
	s_mul_i32 s2, s0, 6
	s_sub_u32 s1, s12, s2
	s_bfe_u32 s2, s17, 0x80010
	s_add_u32 s1, s1, s2
	s_lshl_b32 s0, s0, 1
	s_bfe_u32 s2, s17, 0x80008
	s_add_u32 s0, s0, s2
	s_mov_b32 s94, 0

; #define G_STORE(S, bf) { *(uint4*)&s->a[bf][srow][skc] = S##a0; *(uint4*)&s->a[bf][srow + 32][skc] = S##a1; \
;     if (MB == 2) { *(uint4*)&s->a[bf][srow + 64][skc] = S##a2; *(uint4*)&s->a[bf][srow + 96][skc] = S##a3; } \
;     *(uint4*)&s->b[bf][srow][skc] = S##b0; *(uint4*)&s->b[bf][srow + 32][skc] = S##b1; *(uint4*)&s->b[bf][srow + 64][skc] = S##b2; *(uint4*)&s->b[bf][srow + 96][skc] = S##b3; }
; template <int MB, bool PF2 = true>
; DI void gemm_main(const u16* __restrict__ A, int lda, const u16* __restrict__ B, int ldb, int K, f32x16 (&acc)[MB][2], GemmLds* s, int tid) {
;     ...
;   for (int kt = 0; kt < KT; kt += 2) {
;     { const int k2 = min((kt + 2) * 64, klast); G_LOAD(q, k2); }
;     __builtin_amdgcn_sched_barrier(0);
;     G_COMPUTE(0);
;     G_STORE(p, 1);
;     __syncthreads();
;     { const int k3 = min((kt + 3) * 64, klast); G_LOAD(p, k3); }
;     __builtin_amdgcn_sched_barrier(0);
;     G_COMPUTE(1);
;     G_STORE(q, 0);
;     __syncthreads();
; DI void phase_inproj(const Params& p, int l, char* smem, int tid) {
;     ...
;   for (int it = blockIdx.x; it < 272 * 24; it += gridDim.x) {
;     const int mt = it / 24, nt = it % 24, m0 = mt * 128, n0 = nt * 128;
;     f32x16 acc[2][2]; zero_acc<2>(acc);
;     gemm_main<2>(p.xn + (size_t)m0 * 1024, 1024, Wt + (size_t)n0 * 1024, 1024, 1024, acc, s, tid);
.Lip_last:
	s_and_b32 s6, s17, 0xff
	s_add_u32 s6, s12, s6
	s_cmpk_lt_u32 s6, 0x330
	s_cbranch_scc0 .Lip_nopf
	s_mul_hi_u32 s2, s6, 0xaaaaaaab
	s_lshr_b32 s2, s2, 2
	s_mul_i32 s4, s2, 6
	s_sub_u32 s3, s6, s4
	s_bfe_u32 s4, s17, 0x80010
	s_add_u32 s3, s3, s4
	s_lshl_b32 s2, s2, 1
	s_bfe_u32 s4, s17, 0x80008
	s_add_u32 s2, s2, s4
	s_lshl_b32 s2, s2, 18
	s_add_u32 s4, s96, s2
	s_addc_u32 s5, s97, 0
	s_lshl_b32 s3, s3, 18
	s_add_u32 s8, s14, s3
	s_addc_u32 s9, s15, 0
	ds_read_b128 v[82:85], v103 offset:32768
	ds_read_b128 v[90:93], v107 offset:32768
	ds_read_b128 v[86:89], v103 offset:36864
	ds_read_b128 v[94:97], v107 offset:36864
	s_waitcnt lgkmcnt(4)
	s_add_u32 m0, s10, 0x0
	v_mfma_f32_32x32x16_bf16 v[2:17], v[74:77], v[66:69], v[2:17]
	global_load_lds_dwordx4 v98, s[4:5]
	s_add_u32 m0, s10, 0x400
	v_mfma_f32_32x32x16_bf16 v[18:33], v[78:81], v[66:69], v[18:33]
	global_load_lds_dwordx4 v99, s[4:5]
	s_add_u32 m0, s10, 0x800
	v_mfma_f32_32x32x16_bf16 v[34:49], v[74:77], v[70:73], v[34:49]
	global_load_lds_dwordx4 v100, s[4:5]
	s_add_u32 m0, s10, 0xc00
	v_mfma_f32_32x32x16_bf16 v[50:65], v[78:81], v[70:73], v[50:65]
	global_load_lds_dwordx4 v101, s[4:5]
	s_add_u32 s4, s4, 128
	s_addc_u32 s5, s5, 0
	ds_read_b128 v[66:69], v104 offset:32768
	ds_read_b128 v[74:77], v108 offset:32768
	ds_read_b128 v[70:73], v104 offset:36864
	ds_read_b128 v[78:81], v108 offset:36864
	s_waitcnt lgkmcnt(4)
	s_add_u32 m0, s10, 0x4000
	v_mfma_f32_32x32x16_bf16 v[2:17], v[90:93], v[82:85], v[2:17]
	global_load_lds_dwordx4 v98, s[8:9]
	s_add_u32 m0, s10, 0x4400
	v_mfma_f32_32x32x16_bf16 v[18:33], v[94:97], v[82:85], v[18:33]
	global_load_lds_dwordx4 v99, s[8:9]
	s_add_u32 m0, s10, 0x4800
	v_mfma_f32_32x32x16_bf16 v[34:49], v[90:93], v[86:89], v[34:49]
	global_load_lds_dwordx4 v100, s[8:9]
	s_add_u32 m0, s10, 0x4c00
	v_mfma_f32_32x32x16_bf16 v[50:65], v[94:97], v[86:89], v[50:65]
	global_load_lds_dwordx4 v101, s[8:9]
	s_add_u32 s8, s8, 128
	s_addc_u32 s9, s9, 0
	ds_read_b128 v[82:85], v105 offset:32768
	ds_read_b128 v[90:93], v109 offset:32768
	ds_read_b128 v[86:89], v105 offset:36864
	ds_read_b128 v[94:97], v109 offset:36864
	s_waitcnt lgkmcnt(4)
	v_mfma_f32_32x32x16_bf16 v[2:17], v[74:77], v[66:69], v[2:17]
	v_mfma_f32_32x32x16_bf16 v[18:33], v[78:81], v[66:69], v[18:33]
	v_mfma_f32_32x32x16_bf16 v[34:49], v[74:77], v[70:73], v[34:49]
	v_mfma_f32_32x32x16_bf16 v[50:65], v[78:81], v[70:73], v[50:65]
	s_waitcnt lgkmcnt(0)
	s_barrier
	v_mfma_f32_32x32x16_bf16 v[2:17], v[90:93], v[82:85], v[2:17]
	v_mfma_f32_32x32x16_bf16 v[18:33], v[94:97], v[82:85], v[18:33]
	v_mfma_f32_32x32x16_bf16 v[34:49], v[90:93], v[86:89], v[34:49]
	v_mfma_f32_32x32x16_bf16 v[50:65], v[94:97], v[86:89], v[50:65]
	s_branch .Lip_kdone
